# stack: + attention xhalf exchanges on v_permlane32_swap, sample-unit window tiles rotated one wave, stream row reductions on permlane/DPP, half of the workgroups run sample attention before prompt att
# baseline (speedup 1.0000x reference)
.LBB0_1273:
	s_cmp_lt_i32 s94, 6
	s_cselect_b64 s[2:3], -1, 0
	s_and_b64 s[0:1], s[2:3], s[0:1]
	s_andn2_b64 vcc, exec, s[0:1]
	s_cbranch_vccnz .LBB0_1597
	v_writelane_b32 v253, s2, 47
	s_cmpk_gt_i32 s70, 0x3ff
	v_lshlrev_b32_e32 v141, 3, v0
	v_writelane_b32 v253, s3, 48
	v_writelane_b32 v253, s68, 38
	s_load_dword s0, s[68:69], 0xe0
	v_or_b32_e32 v139, 32, v250
	v_writelane_b32 v253, s69, 39
	s_waitcnt lgkmcnt(0)
	v_writelane_b32 v253, s0, 42
	s_mov_b32 s98, 0
	s_cbranch_scc1 .LBB0_1468
	s_bitcmp1_b32 s70, 3
	s_cbranch_scc0 .Lp5_P
	s_mov_b32 s98, 1
	s_branch .LBB0_1468
.Lp5_P:
	v_lshrrev_b32_e32 v145, 3, v0
	s_movk_i32 s0, 0x7f
	v_cmp_ne_u32_e64 s[0:1], s0, v145
	v_mbcnt_lo_u32_b32 v5, -1, 0
	v_and_b32_e32 v1, 31, v0
	v_writelane_b32 v253, s0, 49
	v_mbcnt_hi_u32_b32 v5, -1, v5
	v_bfe_u32 v143, v0, 6, 2
	v_writelane_b32 v253, s1, 50
	s_movk_i32 s0, 0x1f8
	v_cmp_gt_u32_e64 s[0:1], s0, v0
	v_and_or_b32 v147, v145, 32, v1
	v_and_b32_e32 v9, 64, v5
	v_writelane_b32 v253, s0, 51
	v_xor_b32_e32 v7, 32, v5
	v_add_u32_e32 v9, 64, v9
	v_writelane_b32 v253, s1, 52
	s_movk_i32 s0, 0x41
	v_lshl_or_b32 v10, v143, 6, v147
	v_cmp_gt_u32_e64 s[0:1], s0, v0
	v_cmp_lt_i32_e32 vcc, v7, v9
	v_mul_u32_u24_e32 v14, 0x84, v10
	v_xor_b32_e32 v10, 1, v5
	v_writelane_b32 v253, s0, 43
	v_cndmask_b32_e32 v7, v5, v7, vcc
	v_and_b32_e32 v15, 7, v0
	v_cmp_lt_i32_e32 vcc, v10, v9
	s_add_u32 s58, s92, 0x1ce35000
	v_writelane_b32 v253, s1, 44
	v_cmp_eq_u32_e64 s[0:1], 0, v15
	v_cndmask_b32_e32 v10, v5, v10, vcc
	s_addc_u32 s59, s93, 0
	v_writelane_b32 v253, s0, 45
	v_lshlrev_b32_e32 v184, 2, v10
	v_xor_b32_e32 v10, 2, v5
	s_add_u32 s60, s92, 0x12305000
	v_writelane_b32 v253, s1, 46
	v_cmp_lt_i32_e32 vcc, v10, v9
	s_movk_i32 s0, 0x100
	s_addc_u32 s61, s93, 0
	v_cndmask_b32_e32 v10, v5, v10, vcc
	v_cmp_gt_u32_e64 s[14:15], s0, v0
	s_movk_i32 s0, 0xff
	s_add_u32 s62, s92, 0x16505000
	v_lshlrev_b32_e32 v185, 2, v10
	v_xor_b32_e32 v10, 4, v5
	v_cmp_lt_u32_e64 s[16:17], s0, v0
	s_addc_u32 s63, s93, 0
	s_add_i32 s0, 0, 0x14000
	v_mov_b32_e32 v2, 0
	v_mul_u32_u24_e32 v149, 0x110, v1
	v_and_b32_e32 v138, 56, v141
	v_mul_u32_u24_e32 v177, 0x90, v1
	v_cmp_lt_i32_e32 vcc, v10, v9
	v_mul_u32_u24_e32 v190, 0x88, v1
	v_mov_b32_e32 v1, s0
	s_add_u32 s0, s92, 0x1ca35000
	v_cndmask_b32_e32 v5, v5, v10, vcc
	s_movk_i32 s1, 0x2200
	v_writelane_b32 v253, s0, 36
	s_addc_u32 s0, s93, 0
	v_lshlrev_b32_e32 v10, 2, v138
	v_mov_b32_e32 v11, v2
	v_lshrrev_b32_e32 v3, 5, v250
	v_mad_u32_u24 v1, v187, s1, v1
	v_writelane_b32 v253, s0, 40
	v_lshl_add_u64 v[12:13], s[92:93], 0, v[10:11]
	s_mov_b64 s[0:1], 0xd204000
	v_lshlrev_b32_e32 v176, 4, v3
	v_lshlrev_b32_e32 v140, 2, v15
	v_lshlrev_b32_e32 v188, 2, v5
	v_lshlrev_b32_e32 v5, 7, v0
	v_lshl_add_u64 v[150:151], v[12:13], 0, s[0:1]
	s_add_i32 s0, 0, 0x13100
	v_lshlrev_b32_e32 v4, 3, v3
	v_lshlrev_b32_e32 v136, 2, v3
	v_add_u32_e32 v172, 64, v145
	v_lshlrev_b32_e32 v175, 6, v3
	v_or_b32_e32 v3, 0x60, v250
	s_movk_i32 s2, 0x84
	v_mad_u32_u24 v18, v145, 33, v140
	v_or_b32_e32 v142, 2, v140
	v_or_b32_e32 v144, 3, v140
	v_and_b32_e32 v146, 0x7c00, v5
	v_lshrrev_b32_e32 v5, 2, v0
	v_readlane_b32 s36, v253, 20
	v_add_u32_e32 v195, 0, v176
	v_lshl_add_u32 v200, v0, 2, s0
	s_add_i32 s1, 0, 0x11000
	v_lshl_add_u32 v208, v145, 2, s0
	v_lshl_add_u32 v209, v147, 2, s0
	s_add_i32 s0, 0, 0x13200
	v_lshlrev_b32_e32 v6, 10, v145
	v_lshlrev_b32_e32 v8, 10, v172
	v_mul_u32_u24_e32 v3, 0x90, v3
	v_lshlrev_b32_e32 v179, 2, v7
	v_mul_u32_u24_e32 v7, 0x110, v139
	v_mul_u32_u24_e32 v16, 33, v145
	v_mul_u32_u24_e32 v17, 0x84, v145
	v_mad_u32_u24 v19, v145, 33, v142
	s_waitcnt vmcnt(0)
	v_mad_u32_u24 v20, v145, 33, v144
	v_and_b32_e32 v189, 62, v5
	v_add3_u32 v193, v1, v149, v176
	v_readlane_b32 s37, v253, 21
	v_readlane_b32 s38, v253, 22
	v_readlane_b32 s39, v253, 23
	v_readlane_b32 s40, v253, 24
	v_readlane_b32 s41, v253, 25
	v_readlane_b32 s42, v253, 26
	v_readlane_b32 s43, v253, 27
	v_readlane_b32 s44, v253, 28
	v_readlane_b32 s45, v253, 29
	v_readlane_b32 s46, v253, 30
	v_readlane_b32 s47, v253, 31
	v_readlane_b32 s48, v253, 32
	v_readlane_b32 s49, v253, 33
	v_readlane_b32 s50, v253, 34
	v_readlane_b32 s51, v253, 35
	v_lshl_add_u32 v194, v138, 1, 0
	v_sub_u32_e32 v197, v195, v4
	v_mad_u32_u24 v5, v145, s2, 0
	v_lshlrev_b32_e32 v1, 4, v15
	v_lshl_add_u32 v203, v18, 2, s1
	s_mov_b32 s64, 2.0
	v_writelane_b32 v253, s0, 53
	v_mul_u32_u24_e32 v173, 0x90, v145
	v_mul_u32_u24_e32 v174, 0x110, v138
	v_mul_u32_u24_e32 v178, 0x90, v139
	s_mov_b32 s57, 0
	v_cmp_gt_u32_e64 s[10:11], 32, v250
	v_lshlrev_b32_e64 v180, v140, 1
	v_lshlrev_b32_e64 v181, v140, 2
	v_lshlrev_b32_e64 v182, v140, 4
	v_lshlrev_b32_e64 v183, v140, 8
	v_lshlrev_b32_e32 v148, 9, v145
	v_mul_u32_u24_e32 v191, 0x88, v139
	v_mul_u32_u24_e32 v192, 0x88, v138
	v_lshl_add_u64 v[152:153], s[36:37], 0, v[10:11]
	v_sub_u32_e32 v196, 0, v4
	v_add3_u32 v198, 0, v14, v136
	v_lshl_add_u32 v199, v145, 1, 0
	v_lshl_add_u32 v201, v16, 2, v194
	v_add_u32_e32 v202, v5, v1
	v_add_u32_e32 v204, 4, v203
	v_lshl_add_u32 v205, v19, 2, s1
	v_lshl_add_u32 v206, v20, 2, s1
	v_add3_u32 v207, s1, v17, v1
	v_mov_b32_e32 v1, v140
	v_mov_b32_e32 v135, v142
	v_mov_b32_e32 v137, v144
	v_add_u32_e32 v210, 0x1101c, v5
	v_add_u32_e32 v211, 0x11004, v5
	v_add_u32_e32 v212, 0x11000, v5
	v_lshlrev_b32_e32 v154, 1, v4
	v_lshlrev_b32_e32 v156, 1, v6
	v_lshlrev_b32_e32 v158, 1, v8
	s_mov_b32 s96, 0xffff0000
	v_mov_b32_e32 v213, 0x358637bd
	s_mov_b32 s97, 0xf149f2ca
	s_mov_b32 s65, 0x40400000
	s_mov_b32 s46, 0xe0ad78ec
	s_mov_b64 s[66:67], 0x8000
	s_mov_b64 s[68:69], 0x200
	s_movk_i32 s47, 0x201
	v_lshlrev_b32_e32 v160, 1, v136
	v_mov_b32_e32 v214, 0xf149f2ca
	v_add_u32_e32 v215, v195, v3
	v_add_u32_e32 v216, v197, v7
	v_readlane_b32 s33, v253, 19
	s_mov_b64 s[70:71], 0x600
	s_branch .LBB0_1277

.LBB0_1468:
	v_readlane_b32 s70, v253, 19
	v_readlane_b32 s68, v253, 38
	v_readlane_b32 s44, v253, 20
	v_readlane_b32 s2, v253, 47
	s_cmpk_gt_i32 s70, 0x1ff
	v_readlane_b32 s69, v253, 39
	v_readlane_b32 s45, v253, 21
	v_readlane_b32 s54, v253, 30
	v_readlane_b32 s55, v253, 31
	v_readlane_b32 s56, v253, 32
	v_readlane_b32 s57, v253, 33
	v_readlane_b32 s58, v253, 34
	v_readlane_b32 s59, v253, 35
	v_readlane_b32 s3, v253, 48
	v_readlane_b32 s46, v253, 22
	v_readlane_b32 s47, v253, 23
	v_readlane_b32 s48, v253, 24
	v_readlane_b32 s49, v253, 25
	v_readlane_b32 s50, v253, 26
	v_readlane_b32 s51, v253, 27
	v_readlane_b32 s52, v253, 28
	v_readlane_b32 s53, v253, 29
	s_cbranch_scc1 .LBB0_1597
	s_cmp_eq_u32 s98, 2
	s_cbranch_scc1 .LBB0_1597
	v_mbcnt_lo_u32_b32 v10, -1, 0
	v_mbcnt_hi_u32_b32 v10, -1, v10
	v_and_b32_e32 v13, 64, v10
	v_xor_b32_e32 v12, 1, v10
	v_add_u32_e32 v14, 64, v13
	v_cmp_lt_i32_e32 vcc, v12, v14
	v_lshrrev_b32_e32 v5, 5, v250
	v_and_b32_e32 v7, 7, v0
	v_cndmask_b32_e32 v12, v10, v12, vcc
	v_lshlrev_b32_e32 v189, 2, v12
	v_xor_b32_e32 v12, 2, v10
	v_cmp_lt_i32_e32 vcc, v12, v14
	v_lshrrev_b32_e32 v11, 3, v0
	s_movk_i32 s0, 0x7f
	v_cndmask_b32_e32 v12, v10, v12, vcc
	v_lshlrev_b32_e32 v190, 2, v12
	v_xor_b32_e32 v12, 4, v10
	v_cmp_lt_i32_e32 vcc, v12, v14
	v_cmp_ne_u32_e64 s[4:5], s0, v11
	s_movk_i32 s0, 0x1f8
	v_cndmask_b32_e32 v12, v10, v12, vcc
	v_lshlrev_b32_e32 v191, 2, v12
	v_lshlrev_b32_e32 v12, 6, v5
	v_sub_u32_e32 v12, v7, v12
	v_add_u32_e32 v12, 0x7e1, v12
	v_cmp_gt_u32_e64 s[0:1], s0, v0
	v_cvt_f32_u32_e32 v153, v12
	v_or_b32_e32 v12, 0x60, v250
	v_writelane_b32 v253, s0, 43
	v_mul_u32_u24_e32 v19, 0x90, v12
	v_xor_b32_e32 v12, 32, v10
	v_writelane_b32 v253, s1, 44
	s_movk_i32 s0, 0x200
	v_cmp_lt_i32_e32 vcc, v12, v14
	v_cmp_gt_u32_e64 s[0:1], s0, v0
	v_and_b32_e32 v3, 31, v0
	v_cndmask_b32_e32 v12, v10, v12, vcc
	v_writelane_b32 v253, s0, 36
	v_lshlrev_b32_e32 v194, 2, v12
	v_xor_b32_e32 v12, 8, v10
	v_writelane_b32 v253, s1, 37
	s_movk_i32 s0, 0x100
	v_cmp_lt_i32_e32 vcc, v12, v14
	v_cmp_gt_u32_e64 s[0:1], s0, v0
	v_or_b32_e32 v151, 0x4000, v7
	v_cndmask_b32_e32 v12, v10, v12, vcc
	v_writelane_b32 v253, s0, 40
	v_lshlrev_b32_e32 v195, 2, v12
	v_xor_b32_e32 v12, 16, v10
	v_writelane_b32 v253, s1, 41
	v_cmp_lt_i32_e32 vcc, v12, v14
	v_cmp_gt_u32_e64 s[0:1], 8, v3
	v_or_b32_e32 v188, 0x800, v7
	v_cndmask_b32_e32 v10, v10, v12, vcc
	v_writelane_b32 v253, s0, 55
	v_lshlrev_b32_e32 v196, 2, v10
	v_lshrrev_b32_e32 v10, 1, v0
	v_writelane_b32 v253, s1, 56
	v_cmp_gt_u32_e64 s[0:1], 64, v0
	v_and_b32_e32 v24, 28, v10
	v_or_b32_e32 v10, 2, v24
	v_writelane_b32 v253, s0, 57
	v_mul_u32_u24_e32 v22, 0x84, v7
	v_or_b32_e32 v203, 0x200, v7
	v_writelane_b32 v253, s1, 58
	v_cmp_lt_u32_e64 s[0:1], 4, v24
	v_lshrrev_b32_e32 v204, 4, v250
	v_lshlrev_b32_e32 v4, 3, v5
	v_writelane_b32 v253, s0, 59
	v_mov_b32_e32 v2, 0
	v_and_b32_e32 v150, 56, v141
	v_writelane_b32 v253, s1, 60
	v_cmp_lt_u32_e64 s[0:1], 5, v24
	v_lshlrev_b32_e32 v18, 4, v5
	v_lshlrev_b32_e32 v23, 9, v5
	v_writelane_b32 v253, s0, 45
	v_lshlrev_b32_e32 v219, 2, v5
	v_lshlrev_b32_e32 v6, 3, v187
	v_writelane_b32 v253, s1, 46
	v_cmp_lt_u32_e64 s[0:1], 6, v24
	v_and_b32_e32 v6, 24, v6
	v_mul_u32_u24_e32 v9, 0x84, v6
	v_writelane_b32 v253, s0, 61
	v_mul_u32_u24_e32 v192, 0x90, v3
	s_waitcnt vmcnt(0)
	v_mul_u32_u24_e32 v20, 0x110, v3
	v_writelane_b32 v253, s1, 62
	v_cmp_lt_u32_e64 s[0:1], 8, v24
	v_mul_u32_u24_e32 v220, 0x88, v3
	v_lshlrev_b32_e32 v3, 2, v3
	v_writelane_b32 v253, s0, 63
	v_lshlrev_b32_e32 v6, 10, v11
	v_add_u32_e32 v234, 0, v18
	v_writelane_b32 v254, s1, 0
	v_cmp_lt_u32_e64 s[0:1], 10, v24
	v_or_b32_e32 v8, 0x10000, v6
	v_mul_u32_u24_e32 v16, 0x90, v11
	v_writelane_b32 v254, s0, 1
	v_mul_u32_u24_e32 v17, 0x110, v150
	v_mul_u32_u24_e32 v21, 0x110, v139
	v_writelane_b32 v254, s1, 2
	v_cmp_lt_u32_e64 s[0:1], 12, v24
	v_mul_u32_u24_e32 v26, 0x90, v204
	v_lshl_add_u32 v11, v11, 1, 0
	v_writelane_b32 v254, s0, 3
	v_bfe_u32 v1, v0, 3, 2
	s_mov_b32 s67, 0
	v_writelane_b32 v254, s1, 4
	v_cmp_lt_u32_e64 s[0:1], 14, v24
	v_mul_u32_u24_e32 v193, 0x90, v139
	v_cmp_gt_u32_e64 s[12:13], 32, v250
	v_writelane_b32 v254, s0, 5
	v_cmp_ne_u32_e64 s[18:19], 0, v24
	v_cmp_lt_u32_e64 s[26:27], 7, v24
	v_writelane_b32 v254, s1, 6
	v_cmp_lt_u32_e64 s[0:1], 16, v24
	v_cmp_lt_u32_e64 s[30:31], 9, v24
	v_cmp_lt_u32_e64 s[36:37], 11, v24
	v_writelane_b32 v254, s0, 7
	v_cmp_lt_u32_e64 s[40:41], 13, v24
	v_cmp_lt_u32_e64 s[48:49], 15, v24
	v_writelane_b32 v254, s1, 8
	v_cmp_lt_u32_e64 s[0:1], 18, v24
	v_cmp_lt_u32_e64 s[52:53], 17, v24
	v_cmp_lt_u32_e64 s[56:57], 19, v24
	v_writelane_b32 v254, s0, 9
	v_cmp_lt_u32_e64 s[22:23], 21, v24
	v_cmp_lt_u32_e64 s[60:61], 23, v24
	v_writelane_b32 v254, s1, 10
	v_cmp_lt_u32_e64 s[0:1], 20, v24
	v_cmp_lt_u32_e64 s[64:65], 25, v24
	v_cmp_eq_u32_e64 s[68:69], 28, v24
	v_writelane_b32 v254, s0, 11
	v_lshlrev_b32_e64 v197, v24, 1
	v_lshlrev_b32_e64 v198, v24, 2
	v_writelane_b32 v254, s1, 12
	v_cmp_lt_u32_e64 s[0:1], 22, v24
	v_lshlrev_b32_e64 v199, v24, 4
	v_lshlrev_b32_e64 v200, v24, 8
	v_writelane_b32 v254, s0, 13
	v_add_u32_e32 v202, 1, v187
	v_and_b32_e32 v202, 7, v202
	v_or_b32_e32 v202, -8, v202
	v_mov_b32_e32 v155, v2
	v_writelane_b32 v254, s1, 14
	v_cmp_lt_u32_e64 s[0:1], 24, v24
	v_mov_b32_e32 v159, v2
	v_mul_u32_u24_e32 v221, 0x88, v139
	v_writelane_b32 v254, s0, 15
	v_mov_b32_e32 v157, v2
	v_lshlrev_b32_e32 v164, 1, v4
	v_writelane_b32 v254, s1, 16
	v_cmp_lt_u32_e64 s[0:1], 26, v24
	v_lshlrev_b32_e32 v166, 1, v6
	v_lshlrev_b32_e32 v168, 1, v8
	v_writelane_b32 v254, s0, 17
	v_mov_b32_e32 v237, 0x358637bd
	s_mov_b32 s33, 0xf149f2ca
	v_writelane_b32 v254, s1, 18
	v_cmp_ne_u32_e64 s[0:1], 28, v24
	v_add_u32_e32 v238, v234, v19
	s_mov_b32 s14, 0xe0ad78ec
	v_writelane_b32 v253, s0, 53
	s_movk_i32 s15, 0x201
	v_add_u32_e32 v245, v11, v17
	v_writelane_b32 v253, s1, 54
	v_cmp_lt_u32_e64 s[0:1], 5, v10
	v_mov_b32_e32 v172, 0x41800000
	v_mov_b32_e32 v246, 0xf149f2ca
	v_writelane_b32 v253, s0, 49
	s_nop 1
	v_writelane_b32 v253, s1, 50
	v_cmp_lt_u32_e64 s[0:1], 9, v10
	s_nop 1
	v_writelane_b32 v253, s0, 51
	s_nop 1
	v_writelane_b32 v253, s1, 52
	v_cmp_lt_u32_e64 s[0:1], 13, v10
	s_nop 1
	v_writelane_b32 v254, s0, 19
	s_nop 1
	v_writelane_b32 v254, s1, 20
	v_cmp_lt_u32_e64 s[0:1], 17, v10
	s_nop 1
	v_writelane_b32 v254, s0, 21
	s_nop 1
	v_writelane_b32 v254, s1, 22
	v_cmp_lt_u32_e64 s[0:1], 21, v10
	s_nop 1
	v_writelane_b32 v254, s0, 23
	s_nop 1
	v_writelane_b32 v254, s1, 24
	v_cmp_lt_u32_e64 s[0:1], 25, v10
	v_or_b32_e32 v10, 3, v24
	s_nop 0
	v_writelane_b32 v254, s0, 25
	s_nop 1
	v_writelane_b32 v254, s1, 26
	v_cmp_lt_u32_e64 s[0:1], 4, v10
	s_nop 1
	v_writelane_b32 v254, s0, 27
	s_nop 1
	v_writelane_b32 v254, s1, 28
	v_cmp_lt_u32_e64 s[0:1], 5, v10
	s_nop 1
	v_writelane_b32 v254, s0, 29
	s_nop 1
	v_writelane_b32 v254, s1, 30
	v_cmp_lt_u32_e64 s[0:1], 6, v10
	s_nop 1
	v_writelane_b32 v254, s0, 31
	s_nop 1
	v_writelane_b32 v254, s1, 32
	v_cmp_lt_u32_e64 s[0:1], 8, v10
	s_nop 1
	v_writelane_b32 v254, s0, 33
	s_nop 1
	v_writelane_b32 v254, s1, 34
	v_cmp_lt_u32_e64 s[0:1], 9, v10
	s_nop 1
	v_writelane_b32 v254, s0, 35
	s_nop 1
	v_writelane_b32 v254, s1, 36
	v_cmp_lt_u32_e64 s[0:1], 10, v10
	s_nop 1
	v_writelane_b32 v254, s0, 37
	s_nop 1
	v_writelane_b32 v254, s1, 38
	v_cmp_lt_u32_e64 s[0:1], 12, v10
	s_nop 1
	v_writelane_b32 v254, s0, 39
	s_nop 1
	v_writelane_b32 v254, s1, 40
	v_cmp_lt_u32_e64 s[0:1], 13, v10
	s_nop 1
	v_writelane_b32 v254, s0, 41
	s_nop 1
	v_writelane_b32 v254, s1, 42
	v_cmp_lt_u32_e64 s[0:1], 14, v10
	s_nop 1
	v_writelane_b32 v254, s0, 43
	s_nop 1
	v_writelane_b32 v254, s1, 44
	v_cmp_lt_u32_e64 s[0:1], 16, v10
	s_nop 1
	v_writelane_b32 v254, s0, 45
	s_nop 1
	v_writelane_b32 v254, s1, 46
	v_cmp_lt_u32_e64 s[0:1], 17, v10
	s_nop 1
	v_writelane_b32 v254, s0, 47
	s_nop 1
	v_writelane_b32 v254, s1, 48
	v_cmp_lt_u32_e64 s[0:1], 18, v10
	s_nop 1
	v_writelane_b32 v254, s0, 49
	s_nop 1
	v_writelane_b32 v254, s1, 50
	v_cmp_lt_u32_e64 s[0:1], 20, v10
	s_nop 1
	v_writelane_b32 v254, s0, 51
	s_nop 1
	v_writelane_b32 v254, s1, 52
	v_cmp_lt_u32_e64 s[0:1], 21, v10
	s_nop 1
	v_writelane_b32 v254, s0, 53
	s_nop 1
	v_writelane_b32 v254, s1, 54
	v_cmp_lt_u32_e64 s[0:1], 22, v10
	s_nop 1
	v_writelane_b32 v254, s0, 55
	s_nop 1
	v_writelane_b32 v254, s1, 56
	v_cmp_lt_u32_e64 s[0:1], 24, v10
	s_nop 1
	v_writelane_b32 v254, s0, 57
	s_nop 1
	v_writelane_b32 v254, s1, 58
	v_cmp_lt_u32_e64 s[0:1], 25, v10
	s_nop 1
	v_writelane_b32 v254, s0, 59
	s_nop 1
	v_writelane_b32 v254, s1, 60
	v_cmp_lt_u32_e64 s[0:1], 26, v10
	v_or_b32_e32 v10, v13, v7
	v_lshlrev_b32_e32 v7, 2, v0
	v_writelane_b32 v254, s0, 61
	v_and_b32_e32 v7, 60, v7
	v_lshlrev_b32_e32 v12, 2, v7
	v_writelane_b32 v254, s1, 62
	s_add_u32 s0, s92, 0x12305000
	s_addc_u32 s1, s93, 0
	v_writelane_b32 v254, s0, 63
	s_add_i32 s2, 0, 0x23000
	v_lshl_or_b32 v154, v204, 11, v12
	v_writelane_b32 v255, s1, 0
	s_movk_i32 s0, 0x4600
	v_lshl_or_b32 v156, v204, 12, v12
	v_lshlrev_b32_e32 v12, 1, v204
	v_mad_u32_u24 v5, v187, s0, 0
	s_add_u32 s0, s92, 0x18a35000
	v_or_b32_e32 v205, 8, v12
	v_or_b32_e32 v206, 9, v12
	v_or_b32_e32 v207, 16, v12
	v_or_b32_e32 v208, 17, v12
	v_or_b32_e32 v209, 24, v12
	v_or_b32_e32 v210, 25, v12
	v_or_b32_e32 v211, 32, v12
	v_or_b32_e32 v212, 33, v12
	v_or_b32_e32 v213, 40, v12
	v_or_b32_e32 v214, 41, v12
	v_or_b32_e32 v215, 48, v12
	v_or_b32_e32 v216, 49, v12
	v_or_b32_e32 v217, 56, v12
	v_or_b32_e32 v218, 57, v12
	v_writelane_b32 v255, s0, 1
	s_addc_u32 s0, s93, 0
	v_lshlrev_b32_e32 v12, 2, v150
	v_mov_b32_e32 v13, v2
	v_writelane_b32 v255, s0, 2
	v_lshl_add_u64 v[14:15], s[92:93], 0, v[12:13]
	s_mov_b64 s[0:1], 0xd204000
	v_lshl_add_u64 v[160:161], v[14:15], 0, s[0:1]
	s_add_u32 s0, s92, 0x16505000
	s_addc_u32 s1, s93, 0
	v_writelane_b32 v255, s0, 3
	v_add3_u32 v222, s2, v9, v22
	v_lshl_or_b32 v14, v187, 7, v3
	v_writelane_b32 v255, s1, 4
	s_add_i32 s0, 0, 0x25100
	s_add_i32 s1, 0, 0x10400
	s_add_i32 s2, 0, 0x10000
	v_add_u32_e32 v227, s1, v14
	v_add_u32_e32 v231, s1, v3
	s_add_u32 s1, s90, 0xd574000
	v_writelane_b32 v255, s1, 5
	s_addc_u32 s1, s91, 0
	v_lshlrev_b32_e32 v201, 2, v10
	v_lshrrev_b32_e32 v10, 5, v0
	v_writelane_b32 v255, s1, 6
	s_add_u32 s1, s90, 0xd278000
	v_lshlrev_b32_e32 v25, 9, v10
	v_writelane_b32 v255, s1, 7
	s_addc_u32 s1, s91, 0
	v_add3_u32 v224, s0, v25, v3
	v_add3_u32 v236, s0, v23, v3
	s_add_u32 s0, s92, 0x1ce35000
	v_writelane_b32 v255, s1, 8
	s_addc_u32 s1, s93, 0
	v_lshl_add_u64 v[162:163], s[44:45], 0, v[12:13]
	v_lshl_add_u32 v13, v187, 13, 0
	v_writelane_b32 v255, s0, 9
	v_mul_u32_u24_e32 v27, 0x88, v7
	v_lshlrev_b32_e32 v10, 2, v10
	v_lshl_add_u32 v12, v150, 1, 0
	v_lshl_add_u32 v7, v7, 1, v5
	v_lshl_add_u32 v9, v204, 2, v5
	v_add_u32_e32 v225, v5, v18
	v_add_u32_e32 v5, 0, v3
	v_add3_u32 v230, v13, v23, v3
	v_sub_u32_e32 v13, v234, v4
	v_writelane_b32 v255, s1, 10
	s_mov_b32 s0, 2.0
	v_or_b32_e32 v158, 0x400, v156
	s_mov_b64 s[44:45], s[4:5]
	v_lshl_add_u32 v223, v24, 2, v222
	v_sub_u32_e32 v226, v225, v4
	v_add_u32_e32 v228, s2, v14
	v_add_u32_e32 v229, s2, v3
	v_add_u32_e32 v232, 0x300, v231
	v_add_u32_e32 v233, 0x380, v231
	v_add_u32_e32 v235, v222, v219
	s_mov_b32 s1, 0x40400000
	v_add_u32_e32 v239, v13, v20
	v_add_u32_e32 v240, v13, v21
	v_add_u32_e32 v241, v7, v26
	v_add_u32_e32 v242, v9, v27
	v_add_u32_e32 v243, v5, v25
	v_lshlrev_b32_e32 v170, 1, v10
	v_add_u32_e32 v244, v12, v16
	s_mov_b32 s2, s70
	s_branch .LBB0_1471

.LBB0_1596:
	v_readlane_b32 s68, v253, 38
	v_readlane_b32 s44, v253, 20
	v_readlane_b32 s2, v253, 47
	v_readlane_b32 s70, v253, 19
	v_readlane_b32 s69, v253, 39
	v_readlane_b32 s54, v253, 30
	v_readlane_b32 s55, v253, 31
	v_readlane_b32 s56, v253, 32
	v_readlane_b32 s57, v253, 33
	v_readlane_b32 s58, v253, 34
	v_readlane_b32 s59, v253, 35
	v_readlane_b32 s3, v253, 48
	v_readlane_b32 s45, v253, 21
	v_readlane_b32 s46, v253, 22
	v_readlane_b32 s47, v253, 23
	v_readlane_b32 s48, v253, 24
	v_readlane_b32 s49, v253, 25
	v_readlane_b32 s50, v253, 26
	v_readlane_b32 s51, v253, 27
	v_readlane_b32 s52, v253, 28
	v_readlane_b32 s53, v253, 29
	s_cmp_lg_u32 s98, 1
	s_cbranch_scc1 .LBB0_1597
	s_mov_b32 s98, 2
	v_lshlrev_b32_e32 v141, 3, v0
	v_or_b32_e32 v139, 32, v250
	s_branch .Lp5_P

.LBB0_1732:
	s_andn2_saveexec_b64 s[16:17], s[2:3]
	s_cbranch_execz .LBB0_1725
	v_add_u32_e32 v9, 0xffffc000, v8
	v_cmp_lt_i32_e64 s[2:3], s24, v8
	v_mov_b32_e32 v20, s89
	v_and_b32_e32 v52, 64, v14
	v_cndmask_b32_e64 v8, v8, v9, s[2:3]
	v_mov_b32_e32 v9, s59
	v_cndmask_b32_e64 v21, v9, v20, s[2:3]
	v_mov_b32_e32 v9, s58
	v_mov_b32_e32 v20, s88
	v_cndmask_b32_e64 v20, v9, v20, s[2:3]
	v_ashrrev_i32_e32 v9, 31, v8
	v_lshlrev_b64 v[22:23], 13, v[8:9]
	v_lshl_add_u64 v[20:21], v[20:21], 0, v[22:23]
	v_lshl_add_u64 v[36:37], v[20:21], 0, v[2:3]
	v_add_co_u32_e32 v48, vcc, s23, v36
	global_load_dwordx4 v[20:23], v[36:37], off nt
	global_load_dwordx4 v[24:27], v[36:37], off offset:1024 nt
	global_load_dwordx4 v[28:31], v[36:37], off offset:2048 nt
	global_load_dwordx4 v[32:35], v[36:37], off offset:3072 nt
	v_addc_co_u32_e32 v49, vcc, 0, v37, vcc
	global_load_dwordx4 v[36:39], v[48:49], off nt
	global_load_dwordx4 v[40:43], v[48:49], off offset:1024 nt
	global_load_dwordx4 v[44:47], v[48:49], off offset:2048 nt
	s_nop 0
	global_load_dwordx4 v[48:51], v[48:49], off offset:3072 nt
	v_xor_b32_e32 v53, 32, v14
	v_add_u32_e32 v59, 64, v52
	v_xor_b32_e32 v54, 16, v14
	v_cmp_lt_i32_e32 vcc, v53, v59
	v_xor_b32_e32 v55, 8, v14
	v_xor_b32_e32 v56, 4, v14
	v_cndmask_b32_e32 v52, v14, v53, vcc
	v_cmp_lt_i32_e32 vcc, v54, v59
	v_xor_b32_e32 v57, 2, v14
	v_xor_b32_e32 v58, 1, v14
	v_cndmask_b32_e32 v53, v14, v54, vcc
	v_cmp_lt_i32_e32 vcc, v55, v59
	v_lshlrev_b32_e32 v60, 2, v53
	s_waitcnt vmcnt(7)
	ds_write_b128 v11, v[20:23]
	s_waitcnt vmcnt(6)
	ds_write_b128 v11, v[24:27] offset:1024
	s_waitcnt vmcnt(5)
	ds_write_b128 v11, v[28:31] offset:2048
	s_waitcnt vmcnt(4)
	ds_write_b128 v11, v[32:35] offset:3072
	s_waitcnt vmcnt(3)
	ds_write_b128 v11, v[36:39] offset:4096
	s_waitcnt vmcnt(2)
	ds_write_b128 v11, v[40:43] offset:5120
	s_waitcnt vmcnt(1)
	ds_write_b128 v11, v[44:47] offset:6144
	s_waitcnt vmcnt(0)
	ds_write_b128 v11, v[48:51] offset:7168
	s_waitcnt lgkmcnt(0)
	v_cndmask_b32_e32 v54, v14, v55, vcc
	v_lshlrev_b32_e32 v55, 2, v52
	ds_read_b128 v[22:25], v12
	ds_read_b128 v[26:29], v12 offset:16
	ds_read_b128 v[30:33], v12 offset:32
	ds_read_b128 v[34:37], v12 offset:48
	ds_read_b128 v[38:41], v12 offset:64
	ds_read_b128 v[42:45], v12 offset:80
	ds_read_b128 v[46:49], v12 offset:96
	ds_read_b128 v[50:53], v12 offset:112
	s_waitcnt lgkmcnt(7)
	v_mul_f32_e32 v21, v23, v23
	v_fmac_f32_e32 v21, v22, v22
	v_fmac_f32_e32 v21, v24, v24
	v_fmac_f32_e32 v21, v25, v25
	s_waitcnt lgkmcnt(6)
	v_fmac_f32_e32 v21, v26, v26
	v_fmac_f32_e32 v21, v27, v27
	v_fmac_f32_e32 v21, v28, v28
	v_fmac_f32_e32 v21, v29, v29
	s_waitcnt lgkmcnt(5)
	v_fmac_f32_e32 v21, v30, v30
	v_fmac_f32_e32 v21, v31, v31
	v_fmac_f32_e32 v21, v32, v32
	v_fmac_f32_e32 v21, v33, v33
	s_waitcnt lgkmcnt(4)
	v_fmac_f32_e32 v21, v34, v34
	v_fmac_f32_e32 v21, v35, v35
	v_max3_f32 v20, |v22|, 0, |v23|
	v_fmac_f32_e32 v21, v36, v36
	v_max3_f32 v20, v20, |v24|, |v25|
	v_fmac_f32_e32 v21, v37, v37
	v_max3_f32 v20, v20, |v26|, |v27|
	s_waitcnt lgkmcnt(3)
	v_fmac_f32_e32 v21, v38, v38
	v_max3_f32 v20, v20, |v28|, |v29|
	v_fmac_f32_e32 v21, v39, v39
	v_max3_f32 v20, v20, |v30|, |v31|
	v_fmac_f32_e32 v21, v40, v40
	v_max3_f32 v20, v20, |v32|, |v33|
	v_fmac_f32_e32 v21, v41, v41
	v_max3_f32 v20, v20, |v34|, |v35|
	s_waitcnt lgkmcnt(2)
	v_fmac_f32_e32 v21, v42, v42
	v_max3_f32 v20, v20, |v36|, |v37|
	v_fmac_f32_e32 v21, v43, v43
	v_max3_f32 v20, v20, |v38|, |v39|
	v_fmac_f32_e32 v21, v44, v44
	v_max3_f32 v20, v20, |v40|, |v41|
	v_fmac_f32_e32 v21, v45, v45
	v_max3_f32 v20, v20, |v42|, |v43|
	s_waitcnt lgkmcnt(1)
	v_fmac_f32_e32 v21, v46, v46
	v_max3_f32 v20, v20, |v44|, |v45|
	v_fmac_f32_e32 v21, v47, v47
	v_max3_f32 v20, v20, |v46|, |v47|
	v_fmac_f32_e32 v21, v48, v48
	v_max3_f32 v20, v20, |v48|, |v49|
	v_fmac_f32_e32 v21, v49, v49
	s_waitcnt lgkmcnt(0)
	v_max3_f32 v20, v20, |v50|, |v51|
	v_fmac_f32_e32 v21, v50, v50
	v_max3_f32 v20, v20, |v52|, |v53|
	v_fmac_f32_e32 v21, v51, v51
	v_fmac_f32_e32 v21, v52, v52
	v_fmac_f32_e32 v21, v53, v53
	v_mov_b32_e32 v54, v20
	v_mov_b32_e32 v55, v21
	s_nop 1
	v_permlane32_swap_b32_e32 v54, v20
	v_permlane32_swap_b32_e32 v55, v21
	v_max_f32_e32 v20, v20, v54
	v_add_f32_e32 v21, v21, v55
	v_mov_b32_e32 v54, v20
	v_mov_b32_e32 v55, v21
	s_nop 1
	v_permlane16_swap_b32_e32 v54, v20
	v_permlane16_swap_b32_e32 v55, v21
	v_max_f32_e32 v20, v20, v54
	v_add_f32_e32 v21, v21, v55
	s_nop 0
	v_max_f32_dpp v20, v20, v20 row_ror:8 row_mask:0xf bank_mask:0xf
	v_add_f32_dpp v21, v21, v21 row_ror:8 row_mask:0xf bank_mask:0xf
	s_nop 0
	v_max_f32_dpp v20, v20, v20 row_ror:4 row_mask:0xf bank_mask:0xf
	v_add_f32_dpp v21, v21, v21 row_ror:4 row_mask:0xf bank_mask:0xf
	s_nop 0
	v_max_f32_dpp v20, v20, v20 row_ror:2 row_mask:0xf bank_mask:0xf
	v_add_f32_dpp v21, v21, v21 row_ror:2 row_mask:0xf bank_mask:0xf
	s_nop 0
	v_max_f32_dpp v20, v20, v20 row_ror:1 row_mask:0xf bank_mask:0xf
	v_add_f32_dpp v21, v21, v21 row_ror:1 row_mask:0xf bank_mask:0xf
	v_mul_f32_e32 v21, 0x3a000000, v21
	v_mul_f32_e32 v54, 0x4f800000, v21
	v_cmp_gt_f32_e32 vcc, s25, v21
	s_nop 1
	v_cndmask_b32_e32 v21, v21, v54, vcc
	v_sqrt_f32_e32 v54, v21
	v_mul_f32_e32 v20, 0x3e000000, v20
	v_add_u32_e32 v55, -1, v54
	v_add_u32_e32 v56, 1, v54
	v_fma_f32 v57, -v55, v54, v21
	v_fma_f32 v58, -v56, v54, v21
	v_cmp_ge_f32_e64 s[4:5], 0, v57
	s_nop 1
	v_cndmask_b32_e64 v54, v54, v55, s[4:5]
	v_cmp_lt_f32_e64 s[4:5], 0, v58
	s_nop 1
	v_cndmask_b32_e64 v54, v54, v56, s[4:5]
	v_mul_f32_e32 v55, 0x37800000, v54
	v_cndmask_b32_e32 v54, v54, v55, vcc
	v_cmp_class_f32_e32 vcc, v21, v13
	s_nop 1
	v_cndmask_b32_e32 v21, v54, v21, vcc
	v_mul_f32_e32 v21, 0.5, v21
	v_max3_f32 v20, v21, v20, s26
	v_div_scale_f32 v21, s[4:5], v20, v20, 1.0
	v_rcp_f32_e32 v54, v21
	v_div_scale_f32 v55, vcc, 1.0, v20, 1.0
	v_fma_f32 v56, -v21, v54, 1.0
	v_fmac_f32_e32 v54, v56, v54
	v_mul_f32_e32 v56, v55, v54
	v_fma_f32 v57, -v21, v56, v55
	v_fmac_f32_e32 v56, v57, v54
	v_fma_f32 v21, -v21, v56, v55
	v_div_fmas_f32 v21, v21, v54, v56
	v_div_fixup_f32 v21, v21, v20, 1.0
	v_mul_f32_e32 v22, v22, v21
	v_med3_f32 v54, v22, s27, v15
	v_mul_f32_e32 v22, v28, v21
	v_med3_f32 v28, v22, s27, v15
	v_mul_f32_e32 v22, v29, v21
	v_med3_f32 v29, v22, s27, v15
	v_mul_f32_e32 v22, v30, v21
	v_med3_f32 v30, v22, s27, v15
	v_mul_f32_e32 v22, v31, v21
	v_med3_f32 v31, v22, s27, v15
	v_mul_f32_e32 v22, v32, v21
	v_med3_f32 v32, v22, s27, v15
	v_mul_f32_e32 v22, v33, v21
	v_med3_f32 v33, v22, s27, v15
	v_mul_f32_e32 v22, v34, v21
	v_med3_f32 v34, v22, s27, v15
	v_mul_f32_e32 v22, v35, v21
	v_med3_f32 v35, v22, s27, v15
	v_mul_f32_e32 v22, v36, v21
	v_med3_f32 v36, v22, s27, v15
	v_mul_f32_e32 v22, v37, v21
	v_med3_f32 v37, v22, s27, v15
	v_mul_f32_e32 v22, v38, v21
	v_med3_f32 v38, v22, s27, v15
	v_mul_f32_e32 v22, v39, v21
	v_med3_f32 v39, v22, s27, v15
	v_mul_f32_e32 v22, v40, v21
	v_med3_f32 v40, v22, s27, v15
	v_mul_f32_e32 v22, v41, v21
	v_med3_f32 v41, v22, s27, v15
	v_mul_f32_e32 v22, v42, v21
	v_med3_f32 v42, v22, s27, v15
	v_mul_f32_e32 v22, v43, v21
	v_med3_f32 v43, v22, s27, v15
	v_mul_f32_e32 v22, v44, v21
	v_med3_f32 v44, v22, s27, v15
	v_mul_f32_e32 v22, v45, v21
	v_med3_f32 v45, v22, s27, v15
	v_mul_f32_e32 v22, v46, v21
	v_med3_f32 v46, v22, s27, v15
	v_mul_f32_e32 v22, v47, v21
	v_med3_f32 v47, v22, s27, v15
	v_mul_f32_e32 v22, v48, v21
	v_med3_f32 v48, v22, s27, v15
	v_mul_f32_e32 v22, v49, v21
	v_med3_f32 v49, v22, s27, v15
	v_mul_f32_e32 v22, v50, v21
	v_med3_f32 v50, v22, s27, v15
	v_mul_f32_e32 v22, v51, v21
	v_mul_f32_e32 v23, v23, v21
	v_med3_f32 v51, v22, s27, v15
	v_mul_f32_e32 v22, v52, v21
	v_mul_f32_e32 v24, v24, v21
	v_mul_f32_e32 v25, v25, v21
	v_med3_f32 v23, v23, s27, v15
	v_med3_f32 v52, v22, s27, v15
	v_mov_b32_e32 v22, v3
	v_mul_f32_e32 v26, v26, v21
	v_mul_f32_e32 v27, v27, v21
	v_med3_f32 v24, v24, s27, v15
	v_med3_f32 v25, v25, s27, v15
	v_cvt_scalef32_pk_fp4_f32 v22, v54, v23, 1.0
	v_med3_f32 v26, v26, s27, v15
	v_med3_f32 v27, v27, s27, v15
	v_cvt_scalef32_pk_fp4_f32 v22, v24, v25, 1.0 op_sel:[0,0,1,0]
	v_mov_b32_e32 v23, v3
	v_mov_b32_e32 v24, v3
	v_mov_b32_e32 v25, v3
	v_cvt_scalef32_pk_fp4_f32 v22, v26, v27, 1.0 op_sel:[0,0,0,1]
	v_cvt_scalef32_pk_fp4_f32 v23, v30, v31, 1.0
	v_cvt_scalef32_pk_fp4_f32 v24, v38, v39, 1.0
	v_cvt_scalef32_pk_fp4_f32 v25, v46, v47, 1.0
	v_cndmask_b32_e64 v26, v16, v17, s[2:3]
	v_mov_b32_e32 v27, v3
	v_mul_f32_e32 v21, v53, v21
	v_cvt_scalef32_pk_fp4_f32 v22, v28, v29, 1.0 op_sel:[0,0,1,1]
	v_cvt_scalef32_pk_fp4_f32 v23, v32, v33, 1.0 op_sel:[0,0,1,0]
	v_cvt_scalef32_pk_fp4_f32 v24, v40, v41, 1.0 op_sel:[0,0,1,0]
	v_cvt_scalef32_pk_fp4_f32 v25, v48, v49, 1.0 op_sel:[0,0,1,0]
	v_lshl_add_u64 v[26:27], s[92:93], 0, v[26:27]
	v_lshlrev_b64 v[28:29], 10, v[8:9]
	v_med3_f32 v21, v21, s27, v15
	v_cvt_scalef32_pk_fp4_f32 v23, v34, v35, 1.0 op_sel:[0,0,0,1]
	v_cvt_scalef32_pk_fp4_f32 v24, v42, v43, 1.0 op_sel:[0,0,0,1]
	v_cvt_scalef32_pk_fp4_f32 v25, v50, v51, 1.0 op_sel:[0,0,0,1]
	v_lshl_add_u64 v[26:27], v[26:27], 0, v[28:29]
	v_cvt_scalef32_pk_fp4_f32 v23, v36, v37, 1.0 op_sel:[0,0,1,1]
	v_cvt_scalef32_pk_fp4_f32 v24, v44, v45, 1.0 op_sel:[0,0,1,1]
	v_cvt_scalef32_pk_fp4_f32 v25, v52, v21, 1.0 op_sel:[0,0,1,1]
	v_lshl_add_u64 v[26:27], v[26:27], 0, v[6:7]
	global_store_dwordx4 v[26:27], v[22:25], off
	s_and_saveexec_b64 s[4:5], s[0:1]
	s_cbranch_execz .LBB0_1724
	v_cndmask_b32_e64 v22, v18, v19, s[2:3]
	v_mov_b32_e32 v23, v3
	v_lshl_add_u64 v[22:23], s[92:93], 0, v[22:23]
	v_lshl_add_u64 v[8:9], v[8:9], 2, v[22:23]
	global_store_dword v[8:9], v20, off
	s_branch .LBB0_1724

.LBB0_1898:
	s_andn2_saveexec_b64 s[16:17], s[2:3]
	s_cbranch_execz .LBB0_1891
	v_add_u32_e32 v9, 0xffffc000, v8
	v_cmp_lt_i32_e64 s[2:3], s24, v8
	v_mov_b32_e32 v21, s89
	v_xor_b32_e32 v56, 8, v15
	v_cndmask_b32_e64 v8, v8, v9, s[2:3]
	v_mov_b32_e32 v9, s59
	v_cndmask_b32_e64 v23, v9, v21, s[2:3]
	v_mov_b32_e32 v9, s58
	v_mov_b32_e32 v21, s88
	v_cndmask_b32_e64 v22, v9, v21, s[2:3]
	v_ashrrev_i32_e32 v9, 31, v8
	v_lshlrev_b64 v[24:25], 13, v[8:9]
	v_lshl_add_u64 v[22:23], v[22:23], 0, v[24:25]
	v_lshl_add_u64 v[38:39], v[22:23], 0, v[2:3]
	v_add_co_u32_e32 v54, vcc, s23, v38
	global_load_dwordx4 v[22:25], v[38:39], off nt
	global_load_dwordx4 v[26:29], v[38:39], off offset:1024 nt
	global_load_dwordx4 v[30:33], v[38:39], off offset:2048 nt
	global_load_dwordx4 v[34:37], v[38:39], off offset:3072 nt
	v_addc_co_u32_e32 v55, vcc, 0, v39, vcc
	global_load_dwordx4 v[38:41], v[54:55], off nt
	global_load_dwordx4 v[42:45], v[54:55], off offset:1024 nt
	global_load_dwordx4 v[46:49], v[54:55], off offset:2048 nt
	global_load_dwordx4 v[50:53], v[54:55], off offset:3072 nt
	v_and_b32_e32 v21, 64, v15
	v_xor_b32_e32 v54, 32, v15
	v_add_u32_e32 v21, 64, v21
	v_cmp_lt_i32_e32 vcc, v54, v21
	v_xor_b32_e32 v55, 16, v15
	v_xor_b32_e32 v57, 4, v15
	v_cndmask_b32_e32 v54, v15, v54, vcc
	v_lshlrev_b32_e32 v54, 2, v54
	v_cmp_lt_i32_e32 vcc, v55, v21
	v_xor_b32_e32 v58, 2, v15
	v_xor_b32_e32 v59, 1, v15
	v_cndmask_b32_e32 v55, v15, v55, vcc
	v_lshlrev_b32_e32 v55, 2, v55
	v_cmp_lt_i32_e32 vcc, v56, v21
	s_waitcnt vmcnt(7)
	ds_write_b128 v10, v[22:25]
	s_waitcnt vmcnt(6)
	ds_write_b128 v10, v[26:29] offset:1024
	s_waitcnt vmcnt(5)
	ds_write_b128 v10, v[30:33] offset:2048
	s_waitcnt vmcnt(4)
	ds_write_b128 v10, v[34:37] offset:3072
	s_waitcnt vmcnt(3)
	ds_write_b128 v10, v[38:41] offset:4096
	s_waitcnt vmcnt(2)
	ds_write_b128 v10, v[42:45] offset:5120
	s_waitcnt vmcnt(1)
	ds_write_b128 v10, v[46:49] offset:6144
	s_waitcnt vmcnt(0)
	ds_write_b128 v10, v[50:53] offset:7168
	s_waitcnt lgkmcnt(0)
	ds_read_b128 v[22:25], v13
	ds_read_b128 v[26:29], v13 offset:16
	ds_read_b128 v[30:33], v13 offset:32
	ds_read_b128 v[34:37], v13 offset:48
	ds_read_b128 v[38:41], v13 offset:64
	ds_read_b128 v[42:45], v13 offset:80
	ds_read_b128 v[46:49], v13 offset:96
	ds_read_b128 v[50:53], v13 offset:112
	s_waitcnt lgkmcnt(7)
	v_mul_f32_e32 v61, v23, v23
	v_fmac_f32_e32 v61, v22, v22
	v_fmac_f32_e32 v61, v24, v24
	v_fmac_f32_e32 v61, v25, v25
	s_waitcnt lgkmcnt(6)
	v_fmac_f32_e32 v61, v26, v26
	v_fmac_f32_e32 v61, v27, v27
	v_fmac_f32_e32 v61, v28, v28
	v_fmac_f32_e32 v61, v29, v29
	s_waitcnt lgkmcnt(5)
	v_fmac_f32_e32 v61, v30, v30
	v_fmac_f32_e32 v61, v31, v31
	v_fmac_f32_e32 v61, v32, v32
	v_fmac_f32_e32 v61, v33, v33
	s_waitcnt lgkmcnt(4)
	v_fmac_f32_e32 v61, v34, v34
	v_fmac_f32_e32 v61, v35, v35
	v_fmac_f32_e32 v61, v36, v36
	v_max3_f32 v60, |v22|, 0, |v23|
	v_fmac_f32_e32 v61, v37, v37
	v_max3_f32 v60, v60, |v24|, |v25|
	s_waitcnt lgkmcnt(3)
	v_fmac_f32_e32 v61, v38, v38
	v_max3_f32 v60, v60, |v26|, |v27|
	v_fmac_f32_e32 v61, v39, v39
	v_max3_f32 v60, v60, |v28|, |v29|
	v_fmac_f32_e32 v61, v40, v40
	v_max3_f32 v60, v60, |v30|, |v31|
	v_fmac_f32_e32 v61, v41, v41
	v_max3_f32 v60, v60, |v32|, |v33|
	s_waitcnt lgkmcnt(2)
	v_fmac_f32_e32 v61, v42, v42
	v_max3_f32 v60, v60, |v34|, |v35|
	v_fmac_f32_e32 v61, v43, v43
	v_max3_f32 v60, v60, |v36|, |v37|
	v_fmac_f32_e32 v61, v44, v44
	v_max3_f32 v60, v60, |v38|, |v39|
	v_fmac_f32_e32 v61, v45, v45
	v_max3_f32 v60, v60, |v40|, |v41|
	s_waitcnt lgkmcnt(1)
	v_fmac_f32_e32 v61, v46, v46
	v_max3_f32 v60, v60, |v42|, |v43|
	v_fmac_f32_e32 v61, v47, v47
	v_max3_f32 v60, v60, |v44|, |v45|
	v_fmac_f32_e32 v61, v48, v48
	v_max3_f32 v60, v60, |v46|, |v47|
	v_fmac_f32_e32 v61, v49, v49
	v_max3_f32 v60, v60, |v48|, |v49|
	s_waitcnt lgkmcnt(0)
	v_fmac_f32_e32 v61, v50, v50
	v_max3_f32 v60, v60, |v50|, |v51|
	v_fmac_f32_e32 v61, v51, v51
	v_max3_f32 v60, v60, |v52|, |v53|
	v_fmac_f32_e32 v61, v52, v52
	v_fmac_f32_e32 v61, v53, v53
	v_mov_b32_e32 v54, v60
	v_mov_b32_e32 v55, v61
	s_nop 1
	v_permlane32_swap_b32_e32 v54, v60
	v_permlane32_swap_b32_e32 v55, v61
	v_max_f32_e32 v60, v60, v54
	v_add_f32_e32 v61, v61, v55
	v_mov_b32_e32 v54, v60
	v_mov_b32_e32 v55, v61
	s_nop 1
	v_permlane16_swap_b32_e32 v54, v60
	v_permlane16_swap_b32_e32 v55, v61
	v_max_f32_e32 v60, v60, v54
	v_add_f32_e32 v61, v61, v55
	s_nop 0
	v_max_f32_dpp v60, v60, v60 row_ror:8 row_mask:0xf bank_mask:0xf
	v_add_f32_dpp v61, v61, v61 row_ror:8 row_mask:0xf bank_mask:0xf
	s_nop 0
	v_max_f32_dpp v60, v60, v60 row_ror:4 row_mask:0xf bank_mask:0xf
	v_add_f32_dpp v61, v61, v61 row_ror:4 row_mask:0xf bank_mask:0xf
	s_nop 0
	v_max_f32_dpp v60, v60, v60 row_ror:2 row_mask:0xf bank_mask:0xf
	v_add_f32_dpp v61, v61, v61 row_ror:2 row_mask:0xf bank_mask:0xf
	s_nop 0
	v_max_f32_dpp v60, v60, v60 row_ror:1 row_mask:0xf bank_mask:0xf
	v_add_f32_dpp v61, v61, v61 row_ror:1 row_mask:0xf bank_mask:0xf
	v_mul_f32_e32 v54, 0x3a000000, v61
	v_mul_f32_e32 v55, 0x4f800000, v54
	v_cmp_gt_f32_e32 vcc, s25, v54
	v_mov_b32_e32 v21, v60
	s_nop 0
	v_cndmask_b32_e32 v54, v54, v55, vcc
	v_sqrt_f32_e32 v55, v54
	v_mul_f32_e32 v21, 0x3e000000, v21
	v_add_u32_e32 v56, -1, v55
	v_add_u32_e32 v57, 1, v55
	v_fma_f32 v58, -v56, v55, v54
	v_fma_f32 v59, -v57, v55, v54
	v_cmp_ge_f32_e64 s[4:5], 0, v58
	s_nop 1
	v_cndmask_b32_e64 v55, v55, v56, s[4:5]
	v_cmp_lt_f32_e64 s[4:5], 0, v59
	s_nop 1
	v_cndmask_b32_e64 v55, v55, v57, s[4:5]
	v_mul_f32_e32 v56, 0x37800000, v55
	v_cndmask_b32_e32 v55, v55, v56, vcc
	v_cmp_class_f32_e32 vcc, v54, v14
	s_nop 1
	v_cndmask_b32_e32 v54, v55, v54, vcc
	v_mul_f32_e32 v54, 0.5, v54
	v_max3_f32 v21, v54, v21, s26
	v_div_scale_f32 v54, s[4:5], v21, v21, 1.0
	v_rcp_f32_e32 v55, v54
	v_div_scale_f32 v56, vcc, 1.0, v21, 1.0
	v_fma_f32 v57, -v54, v55, 1.0
	v_fmac_f32_e32 v55, v57, v55
	v_mul_f32_e32 v57, v56, v55
	v_fma_f32 v58, -v54, v57, v56
	v_fmac_f32_e32 v57, v58, v55
	v_fma_f32 v54, -v54, v57, v56
	v_div_fmas_f32 v54, v54, v55, v57
	v_div_fixup_f32 v54, v54, v21, 1.0
	v_mul_f32_e32 v22, v22, v54
	v_med3_f32 v55, v22, s27, v16
	v_mul_f32_e32 v22, v28, v54
	v_med3_f32 v28, v22, s27, v16
	v_mul_f32_e32 v22, v29, v54
	v_med3_f32 v29, v22, s27, v16
	v_mul_f32_e32 v22, v30, v54
	v_med3_f32 v30, v22, s27, v16
	v_mul_f32_e32 v22, v31, v54
	v_med3_f32 v31, v22, s27, v16
	v_mul_f32_e32 v22, v32, v54
	v_med3_f32 v32, v22, s27, v16
	v_mul_f32_e32 v22, v33, v54
	v_med3_f32 v33, v22, s27, v16
	v_mul_f32_e32 v22, v34, v54
	v_med3_f32 v34, v22, s27, v16
	v_mul_f32_e32 v22, v35, v54
	v_med3_f32 v35, v22, s27, v16
	v_mul_f32_e32 v22, v36, v54
	v_med3_f32 v36, v22, s27, v16
	v_mul_f32_e32 v22, v37, v54
	v_med3_f32 v37, v22, s27, v16
	v_mul_f32_e32 v22, v38, v54
	v_med3_f32 v38, v22, s27, v16
	v_mul_f32_e32 v22, v39, v54
	v_med3_f32 v39, v22, s27, v16
	v_mul_f32_e32 v22, v40, v54
	v_med3_f32 v40, v22, s27, v16
	v_mul_f32_e32 v22, v41, v54
	v_med3_f32 v41, v22, s27, v16
	v_mul_f32_e32 v22, v42, v54
	v_med3_f32 v42, v22, s27, v16
	v_mul_f32_e32 v22, v43, v54
	v_med3_f32 v43, v22, s27, v16
	v_mul_f32_e32 v22, v44, v54
	v_med3_f32 v44, v22, s27, v16
	v_mul_f32_e32 v22, v45, v54
	v_med3_f32 v45, v22, s27, v16
	v_mul_f32_e32 v22, v46, v54
	v_med3_f32 v46, v22, s27, v16
	v_mul_f32_e32 v22, v47, v54
	v_med3_f32 v47, v22, s27, v16
	v_mul_f32_e32 v22, v48, v54
	v_med3_f32 v48, v22, s27, v16
	v_mul_f32_e32 v22, v49, v54
	v_med3_f32 v49, v22, s27, v16
	v_mul_f32_e32 v22, v50, v54
	v_med3_f32 v50, v22, s27, v16
	v_mul_f32_e32 v22, v51, v54
	v_med3_f32 v51, v22, s27, v16
	v_mul_f32_e32 v22, v52, v54
	v_mul_f32_e32 v23, v23, v54
	v_med3_f32 v52, v22, s27, v16
	v_mul_f32_e32 v22, v53, v54
	v_mul_f32_e32 v24, v24, v54
	v_mul_f32_e32 v25, v25, v54
	v_med3_f32 v23, v23, s27, v16
	v_med3_f32 v53, v22, s27, v16
	v_mov_b32_e32 v22, v3
	v_mul_f32_e32 v26, v26, v54
	v_mul_f32_e32 v27, v27, v54
	v_med3_f32 v24, v24, s27, v16
	v_med3_f32 v25, v25, s27, v16
	v_cvt_scalef32_pk_fp4_f32 v22, v55, v23, 1.0
	v_med3_f32 v26, v26, s27, v16
	v_med3_f32 v27, v27, s27, v16
	v_cvt_scalef32_pk_fp4_f32 v22, v24, v25, 1.0 op_sel:[0,0,1,0]
	v_mov_b32_e32 v23, v3
	v_mov_b32_e32 v24, v3
	v_mov_b32_e32 v25, v3
	v_cvt_scalef32_pk_fp4_f32 v22, v26, v27, 1.0 op_sel:[0,0,0,1]
	v_cvt_scalef32_pk_fp4_f32 v23, v30, v31, 1.0
	v_cvt_scalef32_pk_fp4_f32 v24, v38, v39, 1.0
	v_cvt_scalef32_pk_fp4_f32 v25, v46, v47, 1.0
	v_cndmask_b32_e64 v26, v17, v18, s[2:3]
	v_mov_b32_e32 v27, v3
	v_cvt_scalef32_pk_fp4_f32 v22, v28, v29, 1.0 op_sel:[0,0,1,1]
	v_cvt_scalef32_pk_fp4_f32 v23, v32, v33, 1.0 op_sel:[0,0,1,0]
	v_cvt_scalef32_pk_fp4_f32 v24, v40, v41, 1.0 op_sel:[0,0,1,0]
	v_cvt_scalef32_pk_fp4_f32 v25, v48, v49, 1.0 op_sel:[0,0,1,0]
	v_lshl_add_u64 v[26:27], s[92:93], 0, v[26:27]
	v_lshlrev_b64 v[28:29], 10, v[8:9]
	v_cvt_scalef32_pk_fp4_f32 v23, v34, v35, 1.0 op_sel:[0,0,0,1]
	v_cvt_scalef32_pk_fp4_f32 v24, v42, v43, 1.0 op_sel:[0,0,0,1]
	v_cvt_scalef32_pk_fp4_f32 v25, v50, v51, 1.0 op_sel:[0,0,0,1]
	v_lshl_add_u64 v[26:27], v[26:27], 0, v[28:29]
	v_cvt_scalef32_pk_fp4_f32 v23, v36, v37, 1.0 op_sel:[0,0,1,1]
	v_cvt_scalef32_pk_fp4_f32 v24, v44, v45, 1.0 op_sel:[0,0,1,1]
	v_cvt_scalef32_pk_fp4_f32 v25, v52, v53, 1.0 op_sel:[0,0,1,1]
	v_lshl_add_u64 v[26:27], v[26:27], 0, v[6:7]
	global_store_dwordx4 v[26:27], v[22:25], off
	s_and_saveexec_b64 s[4:5], s[0:1]
	s_cbranch_execz .LBB0_1890
	v_cndmask_b32_e64 v22, v19, v20, s[2:3]
	v_mov_b32_e32 v23, v3
	v_lshl_add_u64 v[22:23], s[92:93], 0, v[22:23]
	v_lshl_add_u64 v[8:9], v[8:9], 2, v[22:23]
	global_store_dword v[8:9], v21, off
	s_branch .LBB0_1890

	.amdhsa_kernel _Z4mega6Params
		.amdhsa_group_segment_fixed_size 0
		.amdhsa_private_segment_fixed_size 0
		.amdhsa_kernarg_size 480
		.amdhsa_user_sgpr_count 2
		.amdhsa_user_sgpr_dispatch_ptr 0
		.amdhsa_user_sgpr_queue_ptr 0
		.amdhsa_user_sgpr_kernarg_segment_ptr 1
		.amdhsa_user_sgpr_dispatch_id 0
		.amdhsa_user_sgpr_kernarg_preload_length 0
		.amdhsa_user_sgpr_kernarg_preload_offset 0
		.amdhsa_user_sgpr_private_segment_size 0
		.amdhsa_uses_dynamic_stack 0
		.amdhsa_enable_private_segment 0
		.amdhsa_system_sgpr_workgroup_id_x 1
		.amdhsa_system_sgpr_workgroup_id_y 0
		.amdhsa_system_sgpr_workgroup_id_z 0
		.amdhsa_system_sgpr_workgroup_info 0
		.amdhsa_system_vgpr_workitem_id 0
		.amdhsa_next_free_vgpr 256
		.amdhsa_next_free_sgpr 102
		.amdhsa_accum_offset 256
		.amdhsa_reserve_vcc 1
		.amdhsa_float_round_mode_32 0
		.amdhsa_float_round_mode_16_64 0
		.amdhsa_float_denorm_mode_32 3
		.amdhsa_float_denorm_mode_16_64 3
		.amdhsa_dx10_clamp 1
		.amdhsa_ieee_mode 1
		.amdhsa_fp16_overflow 0
		.amdhsa_tg_split 0
		.amdhsa_exception_fp_ieee_invalid_op 0
		.amdhsa_exception_fp_denorm_src 0
		.amdhsa_exception_fp_ieee_div_zero 0
		.amdhsa_exception_fp_ieee_overflow 0
		.amdhsa_exception_fp_ieee_underflow 0
		.amdhsa_exception_fp_ieee_inexact 0
		.amdhsa_exception_int_div_zero 0
	.end_amdhsa_kernel

amdhsa.kernels:
  - .agpr_count:     0
    .args:
      - .offset:         0
        .size:           224
        .value_kind:     by_value
      - .offset:         224
        .size:           4
        .value_kind:     hidden_block_count_x
      - .offset:         228
        .size:           4
        .value_kind:     hidden_block_count_y
      - .offset:         232
        .size:           4
        .value_kind:     hidden_block_count_z
      - .offset:         236
        .size:           2
        .value_kind:     hidden_group_size_x
      - .offset:         238
        .size:           2
        .value_kind:     hidden_group_size_y
      - .offset:         240
        .size:           2
        .value_kind:     hidden_group_size_z
      - .offset:         242
        .size:           2
        .value_kind:     hidden_remainder_x
      - .offset:         244
        .size:           2
        .value_kind:     hidden_remainder_y
      - .offset:         246
        .size:           2
        .value_kind:     hidden_remainder_z
      - .offset:         264
        .size:           8
        .value_kind:     hidden_global_offset_x
      - .offset:         272
        .size:           8
        .value_kind:     hidden_global_offset_y
      - .offset:         280
        .size:           8
        .value_kind:     hidden_global_offset_z
      - .offset:         288
        .size:           2
        .value_kind:     hidden_grid_dims
      - .offset:         344
        .size:           4
        .value_kind:     hidden_dynamic_lds_size
    .group_segment_fixed_size: 0
    .kernarg_segment_align: 8
    .kernarg_segment_size: 480
    .language:       OpenCL C
    .language_version:
      - 2
      - 0
    .max_flat_workgroup_size: 512
    .name:           _Z4mega6Params
    .private_segment_fixed_size: 0
    .sgpr_count:     108
    .sgpr_spill_count: 160
    .symbol:         _Z4mega6Params.kd
    .uniform_work_group_size: 1
    .uses_dynamic_stack: false
    .vgpr_count:     256
    .vgpr_spill_count: 0
    .wavefront_size: 64
